# phase 0: software-pipelined adaLN loop (next trip's 8 w_ada loads issued at the top of the current trip; consume register copies)
# speedup vs baseline: 1.0043x; 1.0043x over previous
; __device__ __forceinline__ void phase0(const Ptrs& P, LAS unsigned char* lds, int G) {
;     ...
;       for (int item = blockIdx.x; item < 96; item += G) {
;           const int n0 = item * 32, kh = lane >> 5, col = lane & 31; float acc[16];
; #pragma unroll
;           for (int b = 0; b < 16; ++b) acc[b] = 0.f;
; #pragma unroll 8
;           for (int it = 0; it < 64; ++it) { const int k = wave * 128 + 2 * it + kh; const float wv = __builtin_nontemporal_load(P.w_ada + (size_t)k * 3072 + n0 + col);
; #pragma unroll
;               for (int b = 0; b < 16; ++b) acc[b] += cl[b * 1024 + k] * wv; }
.LBB0_31:
	s_lshl_b32 s2, s7, 5
	s_ashr_i32 s3, s2, 31
	v_lshl_add_u64 v[16:17], s[2:3], 2, v[2:3]
	v_mov_b32_e32 v35, v34
	s_mov_b32 s3, 0
	v_mov_b32_e32 v20, 0
	v_mov_b32_e32 v21, v1
	v_mov_b32_e32 v18, 0
	v_mov_b32_e32 v19, v1
	v_mov_b32_e32 v14, 0
	v_mov_b32_e32 v15, v1
	v_mov_b32_e32 v12, 0
	v_mov_b32_e32 v13, v1
	v_mov_b32_e32 v10, 0
	v_mov_b32_e32 v11, v1
	v_mov_b32_e32 v8, 0
	v_mov_b32_e32 v9, v1
	v_mov_b32_e32 v6, 0
	v_mov_b32_e32 v7, v1
	v_mov_b32_e32 v4, 0
	v_mov_b32_e32 v5, v1
	v_add_u32_e32 v41, s3, v0
	v_add_u32_e32 v160, 2, v41
	v_add_u32_e32 v162, 4, v41
	v_add_u32_e32 v164, 6, v41
	v_add_u32_e32 v166, 8, v41
	v_add_u32_e32 v168, 10, v41
	v_add_u32_e32 v170, 12, v41
	v_add_u32_e32 v172, 14, v41
	v_mad_u64_u32 v[46:47], s[4:5], v41, s6, v[16:17]
	v_mad_u64_u32 v[160:161], s[4:5], v160, s6, v[16:17]
	v_mad_u64_u32 v[162:163], s[4:5], v162, s6, v[16:17]
	v_mad_u64_u32 v[164:165], s[4:5], v164, s6, v[16:17]
	v_mad_u64_u32 v[166:167], s[4:5], v166, s6, v[16:17]
	v_mad_u64_u32 v[168:169], s[4:5], v168, s6, v[16:17]
	v_mad_u64_u32 v[170:171], s[4:5], v170, s6, v[16:17]
	v_mad_u64_u32 v[172:173], s[4:5], v172, s6, v[16:17]
	global_load_dword v46, v[46:47], off nt
	global_load_dword v160, v[160:161], off nt
	global_load_dword v162, v[162:163], off nt
	global_load_dword v164, v[164:165], off nt
	global_load_dword v166, v[166:167], off nt
	global_load_dword v168, v[168:169], off nt
	global_load_dword v170, v[170:171], off nt
	global_load_dword v172, v[172:173], off nt
.LBB0_32:
	s_waitcnt vmcnt(0)
	v_mov_b32_e32 v190, v46
	v_mov_b32_e32 v192, v160
	v_mov_b32_e32 v194, v162
	v_mov_b32_e32 v196, v164
	v_mov_b32_e32 v198, v166
	v_mov_b32_e32 v202, v168
	v_mov_b32_e32 v204, v170
	v_mov_b32_e32 v206, v172
	s_cmpk_eq_i32 s3, 0x70
	s_cbranch_scc1 .Lada_nonext
	v_add_u32_e32 v41, s3, v0
	v_add_u32_e32 v41, 16, v41
	v_add_u32_e32 v160, 2, v41
	v_add_u32_e32 v162, 4, v41
	v_add_u32_e32 v164, 6, v41
	v_add_u32_e32 v166, 8, v41
	v_add_u32_e32 v168, 10, v41
	v_add_u32_e32 v170, 12, v41
	v_add_u32_e32 v172, 14, v41
	v_mad_u64_u32 v[46:47], s[4:5], v41, s6, v[16:17]
	v_mad_u64_u32 v[160:161], s[4:5], v160, s6, v[16:17]
	v_mad_u64_u32 v[162:163], s[4:5], v162, s6, v[16:17]
	v_mad_u64_u32 v[164:165], s[4:5], v164, s6, v[16:17]
	v_mad_u64_u32 v[166:167], s[4:5], v166, s6, v[16:17]
	v_mad_u64_u32 v[168:169], s[4:5], v168, s6, v[16:17]
	v_mad_u64_u32 v[170:171], s[4:5], v170, s6, v[16:17]
	v_mad_u64_u32 v[172:173], s[4:5], v172, s6, v[16:17]
	global_load_dword v46, v[46:47], off nt
	global_load_dword v160, v[160:161], off nt
	global_load_dword v162, v[162:163], off nt
	global_load_dword v164, v[164:165], off nt
	global_load_dword v166, v[166:167], off nt
	global_load_dword v168, v[168:169], off nt
	global_load_dword v170, v[170:171], off nt
	global_load_dword v172, v[172:173], off nt
.Lada_nonext:
	v_add_u32_e32 v36, 0x1000, v35
	v_add_u32_e32 v37, 0x2000, v35
	v_add_u32_e32 v38, 0x3000, v35
	v_add_u32_e32 v39, 0x4000, v35
	v_add_u32_e32 v40, 0x5000, v35
	v_add_u32_e32 v42, 0x6000, v35
	v_add_u32_e32 v43, 0x7000, v35
	v_add_u32_e32 v144, 0x8000, v35
	v_add_u32_e32 v146, 0x9000, v35
	v_add_u32_e32 v148, 0xa000, v35
	v_add_u32_e32 v150, 0xb000, v35
	v_add_u32_e32 v152, 0xc000, v35
	v_add_u32_e32 v154, 0xd000, v35
	v_add_u32_e32 v156, 0xe000, v35
	v_add_u32_e32 v158, 0xf000, v35
	ds_read2_b32 v[22:23], v35 offset1:2
	ds_read2_b32 v[24:25], v35 offset0:4 offset1:6
	ds_read2_b32 v[26:27], v35 offset0:8 offset1:10
	ds_read2_b32 v[44:45], v35 offset0:12 offset1:14
	ds_read2_b32 v[48:49], v36 offset1:2
	ds_read2_b32 v[50:51], v37 offset1:2
	ds_read2_b32 v[52:53], v38 offset1:2
	ds_read2_b32 v[54:55], v39 offset1:2
	ds_read2_b32 v[56:57], v40 offset1:2
	ds_read2_b32 v[58:59], v42 offset1:2
	ds_read2_b32 v[60:61], v43 offset1:2
	ds_read2_b32 v[62:63], v144 offset1:2
	ds_read2_b32 v[64:65], v146 offset1:2
	ds_read2_b32 v[66:67], v148 offset1:2
	ds_read2_b32 v[68:69], v150 offset1:2
	ds_read2_b32 v[70:71], v152 offset1:2
	ds_read2_b32 v[72:73], v154 offset1:2
	ds_read2_b32 v[74:75], v156 offset1:2
	ds_read2_b32 v[76:77], v158 offset1:2
	ds_read2_b32 v[78:79], v36 offset0:4 offset1:6
	ds_read2_b32 v[80:81], v37 offset0:4 offset1:6
	ds_read2_b32 v[82:83], v38 offset0:4 offset1:6
	ds_read2_b32 v[84:85], v39 offset0:4 offset1:6
	ds_read2_b32 v[86:87], v40 offset0:4 offset1:6
	ds_read2_b32 v[88:89], v42 offset0:4 offset1:6
	ds_read2_b32 v[90:91], v43 offset0:4 offset1:6
	ds_read2_b32 v[92:93], v144 offset0:4 offset1:6
	ds_read2_b32 v[94:95], v146 offset0:4 offset1:6
	ds_read2_b32 v[96:97], v148 offset0:4 offset1:6
	ds_read2_b32 v[98:99], v150 offset0:4 offset1:6
	ds_read2_b32 v[100:101], v152 offset0:4 offset1:6
	ds_read2_b32 v[102:103], v154 offset0:4 offset1:6
	ds_read2_b32 v[104:105], v156 offset0:4 offset1:6
	ds_read2_b32 v[106:107], v158 offset0:4 offset1:6
	ds_read2_b32 v[108:109], v36 offset0:8 offset1:10
	ds_read2_b32 v[110:111], v37 offset0:8 offset1:10
	ds_read2_b32 v[112:113], v38 offset0:8 offset1:10
	ds_read2_b32 v[114:115], v39 offset0:8 offset1:10
	ds_read2_b32 v[116:117], v40 offset0:8 offset1:10
	ds_read2_b32 v[118:119], v42 offset0:8 offset1:10
	ds_read2_b32 v[120:121], v43 offset0:8 offset1:10
	ds_read2_b32 v[122:123], v144 offset0:8 offset1:10
	ds_read2_b32 v[124:125], v146 offset0:8 offset1:10
	ds_read2_b32 v[126:127], v148 offset0:8 offset1:10
	ds_read2_b32 v[128:129], v150 offset0:8 offset1:10
	ds_read2_b32 v[130:131], v152 offset0:8 offset1:10
	ds_read2_b32 v[132:133], v154 offset0:8 offset1:10
	ds_read2_b32 v[134:135], v156 offset0:8 offset1:10
	ds_read2_b32 v[136:137], v158 offset0:8 offset1:10
	ds_read2_b32 v[138:139], v36 offset0:12 offset1:14
	ds_read2_b32 v[36:37], v37 offset0:12 offset1:14
	ds_read2_b32 v[140:141], v38 offset0:12 offset1:14
	ds_read2_b32 v[38:39], v39 offset0:12 offset1:14
	ds_read2_b32 v[40:41], v40 offset0:12 offset1:14
	ds_read2_b32 v[142:143], v42 offset0:12 offset1:14
	ds_read2_b32 v[42:43], v43 offset0:12 offset1:14
	ds_read2_b32 v[144:145], v144 offset0:12 offset1:14
	ds_read2_b32 v[146:147], v146 offset0:12 offset1:14
	ds_read2_b32 v[148:149], v148 offset0:12 offset1:14
	ds_read2_b32 v[150:151], v150 offset0:12 offset1:14
	ds_read2_b32 v[152:153], v152 offset0:12 offset1:14
	ds_read2_b32 v[154:155], v154 offset0:12 offset1:14
	ds_read2_b32 v[156:157], v156 offset0:12 offset1:14
	ds_read2_b32 v[158:159], v158 offset0:12 offset1:14
	s_waitcnt lgkmcnt(14)
; __device__ __forceinline__ void phase0(const Ptrs& P, LAS unsigned char* lds, int G) {
;     ...
;           for (int it = 0; it < 64; ++it) { const int k = wave * 128 + 2 * it + kh; const float wv = __builtin_nontemporal_load(P.w_ada + (size_t)k * 3072 + n0 + col);
; #pragma unroll
;               for (int b = 0; b < 16; ++b) acc[b] += cl[b * 1024 + k] * wv; }
	v_mov_b32_e32 v174, v22
	v_mov_b32_e32 v175, v48
	v_mov_b32_e32 v176, v50
	v_mov_b32_e32 v177, v52
	v_mov_b32_e32 v178, v54
	v_mov_b32_e32 v179, v56
	v_mov_b32_e32 v180, v58
	v_mov_b32_e32 v181, v60
	v_mov_b32_e32 v182, v62
	v_mov_b32_e32 v183, v64
	v_mov_b32_e32 v184, v66
	v_mov_b32_e32 v185, v68
	v_mov_b32_e32 v186, v70
	v_mov_b32_e32 v187, v72
	v_mov_b32_e32 v188, v74
	v_mov_b32_e32 v189, v76
	v_mov_b32_e32 v48, v23
	v_mov_b32_e32 v52, v51
	v_mov_b32_e32 v56, v55
	v_mov_b32_e32 v60, v59
	v_mov_b32_e32 v64, v63
	v_mov_b32_e32 v68, v67
	v_mov_b32_e32 v72, v71
	v_mov_b32_e32 v76, v75
	v_mov_b32_e32 v22, v24
	v_mov_b32_e32 v23, v78
	v_mov_b32_e32 v50, v80
	v_mov_b32_e32 v51, v82
	v_mov_b32_e32 v54, v84
	v_mov_b32_e32 v55, v86
	v_mov_b32_e32 v58, v88
	v_mov_b32_e32 v59, v90
	v_mov_b32_e32 v62, v92
	v_mov_b32_e32 v63, v94
	v_mov_b32_e32 v66, v96
	v_mov_b32_e32 v67, v98
	v_mov_b32_e32 v70, v100
	v_mov_b32_e32 v71, v102
	v_mov_b32_e32 v74, v104
	v_mov_b32_e32 v75, v106
	v_mov_b32_e32 v78, v25
	v_mov_b32_e32 v82, v81
	v_mov_b32_e32 v86, v85
	v_mov_b32_e32 v90, v89
	v_mov_b32_e32 v94, v93
	v_mov_b32_e32 v98, v97
	v_mov_b32_e32 v102, v101
	v_mov_b32_e32 v106, v105
	v_mov_b32_e32 v24, v26
	v_mov_b32_e32 v25, v108
	v_mov_b32_e32 v80, v110
	v_mov_b32_e32 v81, v112
	v_mov_b32_e32 v84, v114
	v_mov_b32_e32 v85, v116
	v_mov_b32_e32 v88, v118
	v_mov_b32_e32 v89, v120
	v_mov_b32_e32 v92, v122
	v_mov_b32_e32 v93, v124
	v_mov_b32_e32 v96, v126
	v_mov_b32_e32 v97, v128
	v_mov_b32_e32 v100, v130
	v_mov_b32_e32 v101, v132
	v_mov_b32_e32 v104, v134
	v_mov_b32_e32 v105, v136
	v_mov_b32_e32 v108, v27
	v_mov_b32_e32 v112, v111
	v_mov_b32_e32 v116, v115
	v_mov_b32_e32 v120, v119
	v_mov_b32_e32 v124, v123
	v_mov_b32_e32 v128, v127
	v_mov_b32_e32 v132, v131
	v_mov_b32_e32 v136, v135
	v_pk_fma_f32 v[20:21], v[190:191], v[174:175], v[20:21] op_sel_hi:[0,1,1]
	v_pk_fma_f32 v[18:19], v[190:191], v[176:177], v[18:19] op_sel_hi:[0,1,1]
	v_pk_fma_f32 v[14:15], v[190:191], v[178:179], v[14:15] op_sel_hi:[0,1,1]
	v_pk_fma_f32 v[12:13], v[190:191], v[180:181], v[12:13] op_sel_hi:[0,1,1]
	v_pk_fma_f32 v[10:11], v[190:191], v[182:183], v[10:11] op_sel_hi:[0,1,1]
	v_pk_fma_f32 v[8:9], v[190:191], v[184:185], v[8:9] op_sel_hi:[0,1,1]
	v_pk_fma_f32 v[6:7], v[190:191], v[186:187], v[6:7] op_sel_hi:[0,1,1]
	v_pk_fma_f32 v[4:5], v[190:191], v[188:189], v[4:5] op_sel_hi:[0,1,1]
	v_pk_fma_f32 v[20:21], v[192:193], v[48:49], v[20:21] op_sel_hi:[0,1,1]
	v_pk_fma_f32 v[18:19], v[192:193], v[52:53], v[18:19] op_sel_hi:[0,1,1]
	v_pk_fma_f32 v[14:15], v[192:193], v[56:57], v[14:15] op_sel_hi:[0,1,1]
	v_pk_fma_f32 v[12:13], v[192:193], v[60:61], v[12:13] op_sel_hi:[0,1,1]
	v_pk_fma_f32 v[10:11], v[192:193], v[64:65], v[10:11] op_sel_hi:[0,1,1]
	v_pk_fma_f32 v[8:9], v[192:193], v[68:69], v[8:9] op_sel_hi:[0,1,1]
	v_pk_fma_f32 v[6:7], v[192:193], v[72:73], v[6:7] op_sel_hi:[0,1,1]
	v_pk_fma_f32 v[4:5], v[192:193], v[76:77], v[4:5] op_sel_hi:[0,1,1]
	v_pk_fma_f32 v[20:21], v[194:195], v[22:23], v[20:21] op_sel_hi:[0,1,1]
	v_pk_fma_f32 v[18:19], v[194:195], v[50:51], v[18:19] op_sel_hi:[0,1,1]
	v_pk_fma_f32 v[14:15], v[194:195], v[54:55], v[14:15] op_sel_hi:[0,1,1]
	v_pk_fma_f32 v[12:13], v[194:195], v[58:59], v[12:13] op_sel_hi:[0,1,1]
	v_pk_fma_f32 v[10:11], v[194:195], v[62:63], v[10:11] op_sel_hi:[0,1,1]
	v_pk_fma_f32 v[8:9], v[194:195], v[66:67], v[8:9] op_sel_hi:[0,1,1]
	v_pk_fma_f32 v[6:7], v[194:195], v[70:71], v[6:7] op_sel_hi:[0,1,1]
	v_pk_fma_f32 v[4:5], v[194:195], v[74:75], v[4:5] op_sel_hi:[0,1,1]
	v_pk_fma_f32 v[20:21], v[196:197], v[78:79], v[20:21] op_sel_hi:[0,1,1]
	v_pk_fma_f32 v[18:19], v[196:197], v[82:83], v[18:19] op_sel_hi:[0,1,1]
	v_pk_fma_f32 v[14:15], v[196:197], v[86:87], v[14:15] op_sel_hi:[0,1,1]
	v_pk_fma_f32 v[12:13], v[196:197], v[90:91], v[12:13] op_sel_hi:[0,1,1]
	v_pk_fma_f32 v[10:11], v[196:197], v[94:95], v[10:11] op_sel_hi:[0,1,1]
	v_pk_fma_f32 v[8:9], v[196:197], v[98:99], v[8:9] op_sel_hi:[0,1,1]
	v_pk_fma_f32 v[6:7], v[196:197], v[102:103], v[6:7] op_sel_hi:[0,1,1]
	v_pk_fma_f32 v[4:5], v[196:197], v[106:107], v[4:5] op_sel_hi:[0,1,1]
	v_pk_fma_f32 v[20:21], v[198:199], v[24:25], v[20:21] op_sel_hi:[0,1,1]
	v_pk_fma_f32 v[18:19], v[198:199], v[80:81], v[18:19] op_sel_hi:[0,1,1]
	v_pk_fma_f32 v[14:15], v[198:199], v[84:85], v[14:15] op_sel_hi:[0,1,1]
	v_pk_fma_f32 v[12:13], v[198:199], v[88:89], v[12:13] op_sel_hi:[0,1,1]
	v_pk_fma_f32 v[10:11], v[198:199], v[92:93], v[10:11] op_sel_hi:[0,1,1]
	v_pk_fma_f32 v[8:9], v[198:199], v[96:97], v[8:9] op_sel_hi:[0,1,1]
	v_pk_fma_f32 v[6:7], v[198:199], v[100:101], v[6:7] op_sel_hi:[0,1,1]
	v_pk_fma_f32 v[4:5], v[198:199], v[104:105], v[4:5] op_sel_hi:[0,1,1]
	v_mov_b32_e32 v26, v44
	v_mov_b32_e32 v27, v138
	v_mov_b32_e32 v138, v45
	s_waitcnt lgkmcnt(13)
; __device__ __forceinline__ void phase0(const Ptrs& P, LAS unsigned char* lds, int G) {
;     ...
; #pragma unroll
;               for (int b = 0; b < 16; ++b) acc[b] += cl[b * 1024 + k] * wv; }
; #pragma unroll
;           for (int b = 0; b < 16; ++b) { acc[b] += __shfl_xor(acc[b], 32); if (lane < 32) red[(wave * 16 + b) * 32 + col] = acc[b]; }
	v_mov_b32_e32 v44, v36
	s_waitcnt lgkmcnt(12)
	v_mov_b32_e32 v45, v140
	v_mov_b32_e32 v140, v37
	s_waitcnt lgkmcnt(11)
	v_mov_b32_e32 v36, v38
	s_waitcnt lgkmcnt(10)
	v_mov_b32_e32 v37, v40
	v_mov_b32_e32 v40, v39
	s_waitcnt lgkmcnt(9)
	v_mov_b32_e32 v38, v142
	s_waitcnt lgkmcnt(8)
	v_mov_b32_e32 v39, v42
	s_waitcnt lgkmcnt(7)
	v_mov_b32_e32 v110, v144
	s_waitcnt lgkmcnt(6)
	v_mov_b32_e32 v111, v146
	s_waitcnt lgkmcnt(5)
	v_mov_b32_e32 v114, v148
	s_waitcnt lgkmcnt(4)
	v_mov_b32_e32 v115, v150
	s_waitcnt lgkmcnt(3)
	v_mov_b32_e32 v118, v152
	s_waitcnt lgkmcnt(2)
	v_mov_b32_e32 v119, v154
	s_waitcnt lgkmcnt(1)
	v_mov_b32_e32 v122, v156
	s_waitcnt lgkmcnt(0)
	v_mov_b32_e32 v123, v158
	v_pk_fma_f32 v[20:21], v[202:203], v[108:109], v[20:21] op_sel_hi:[0,1,1]
	v_pk_fma_f32 v[18:19], v[202:203], v[112:113], v[18:19] op_sel_hi:[0,1,1]
	v_pk_fma_f32 v[14:15], v[202:203], v[116:117], v[14:15] op_sel_hi:[0,1,1]
	v_pk_fma_f32 v[12:13], v[202:203], v[120:121], v[12:13] op_sel_hi:[0,1,1]
	v_pk_fma_f32 v[10:11], v[202:203], v[124:125], v[10:11] op_sel_hi:[0,1,1]
	v_pk_fma_f32 v[8:9], v[202:203], v[128:129], v[8:9] op_sel_hi:[0,1,1]
	v_pk_fma_f32 v[6:7], v[202:203], v[132:133], v[6:7] op_sel_hi:[0,1,1]
	v_pk_fma_f32 v[4:5], v[202:203], v[136:137], v[4:5] op_sel_hi:[0,1,1]
	s_add_i32 s3, s3, 16
	v_mov_b32_e32 v42, v143
	v_mov_b32_e32 v146, v145
	v_mov_b32_e32 v150, v149
	v_mov_b32_e32 v154, v153
	v_mov_b32_e32 v158, v157
	v_pk_fma_f32 v[20:21], v[204:205], v[26:27], v[20:21] op_sel_hi:[0,1,1]
	v_pk_fma_f32 v[18:19], v[204:205], v[44:45], v[18:19] op_sel_hi:[0,1,1]
	v_pk_fma_f32 v[14:15], v[204:205], v[36:37], v[14:15] op_sel_hi:[0,1,1]
	v_pk_fma_f32 v[12:13], v[204:205], v[38:39], v[12:13] op_sel_hi:[0,1,1]
	v_pk_fma_f32 v[10:11], v[204:205], v[110:111], v[10:11] op_sel_hi:[0,1,1]
	v_pk_fma_f32 v[8:9], v[204:205], v[114:115], v[8:9] op_sel_hi:[0,1,1]
	v_pk_fma_f32 v[6:7], v[204:205], v[118:119], v[6:7] op_sel_hi:[0,1,1]
	v_pk_fma_f32 v[4:5], v[204:205], v[122:123], v[4:5] op_sel_hi:[0,1,1]
	v_add_u32_e32 v35, 64, v35
	s_cmpk_lg_i32 s3, 0x80
	v_pk_fma_f32 v[20:21], v[206:207], v[138:139], v[20:21] op_sel_hi:[0,1,1]
	v_pk_fma_f32 v[18:19], v[206:207], v[140:141], v[18:19] op_sel_hi:[0,1,1]
	v_pk_fma_f32 v[14:15], v[206:207], v[40:41], v[14:15] op_sel_hi:[0,1,1]
	v_pk_fma_f32 v[12:13], v[206:207], v[42:43], v[12:13] op_sel_hi:[0,1,1]
	v_pk_fma_f32 v[10:11], v[206:207], v[146:147], v[10:11] op_sel_hi:[0,1,1]
	v_pk_fma_f32 v[8:9], v[206:207], v[150:151], v[8:9] op_sel_hi:[0,1,1]
	v_pk_fma_f32 v[6:7], v[206:207], v[154:155], v[6:7] op_sel_hi:[0,1,1]
	v_pk_fma_f32 v[4:5], v[206:207], v[158:159], v[4:5] op_sel_hi:[0,1,1]
	s_cbranch_scc1 .LBB0_32
	ds_bpermute_b32 v16, v30, v20
	s_and_saveexec_b64 s[4:5], vcc
	s_cbranch_execz .LBB0_35
	s_waitcnt lgkmcnt(0)
	v_add_f32_e32 v16, v20, v16
	ds_write_b32 v31, v16
